# v97: v95 + workgroups of an XCD enter each GEMM phase 0..3 us apart (by pm index) to de-synchronise the epilogue store bursts
# baseline (speedup 1.0000x reference)
; #define REP(b) for (int rep_ = 0; rep_ < (((DUPMASK >> (b)) & 1) ? 2 : 1); ++rep_)
; __global__ void __launch_bounds__(NWAVES * 64, 2) fwd(Args args_unused) {
;     ...
;         if (IN(pb)) {
;             REP(2) { ENV(); pg8::Gemm g{(const bf16*)(ws + WS_HN), (const bf16*)(ws + WS_W + (size_t)l * W_LAYER + W_IN), M, NIN, DM, LDH, 0}; pg8::StaticOrder S; S.init(M, NIN, G, bx);
;               pg8::EpiProj E{(bf16*)(ws + WS_PROJ), (const float*)(ws + WS_COSA), (const float*)(ws + WS_SINA), (const float*)(ws + WS_COSB), (const float*)(ws + WS_SINB), (const pg8::ss_t*)(ws + WS_SS) + l * M};
;               pg8::gemm_phase<pg8::EpiProj, pg8::StaticOrder, true>(ldsp + RING_OFF, g, S, E); }
.Ldefer_skipA:
	v_mov_b32_e32 v2, s61
	ds_read_b32 v2, v2
	s_waitcnt lgkmcnt(0)
	v_readfirstlane_b32 s98, v2
	s_and_b32 s98, s98, 3
	s_cmp_eq_u32 s98, 0
	s_cbranch_scc1 .Lstg_done_0
.Lstg_loop_0:
	s_sleep 30
	s_sub_u32 s98, s98, 1
	s_cmp_lg_u32 s98, 0
	s_cbranch_scc1 .Lstg_loop_0

; __global__ void __launch_bounds__(NWAVES * 64, 2) fwd(Args args_unused) {
;     ...
;         if (IN(pb + 3)) {
;             { ENV(); pg8::Gemm g{(const bf16*)(ws + WS_MIX), (const bf16*)(ws + WS_W + (size_t)l * W_LAYER + W_OUT), M, DM, DM, LDMX, 0}; pg8::StaticOrder S; S.init(M, DM, G, bx);
.LBB0_557:
	s_andn2_b64 vcc, exec, s[4:5]
	s_cbranch_vccnz .LBB0_656
	v_mov_b32_e32 v2, s61
	ds_read_b32 v2, v2
	s_waitcnt lgkmcnt(0)
	v_readfirstlane_b32 s98, v2
	s_and_b32 s98, s98, 3
	s_cmp_eq_u32 s98, 0
	s_cbranch_scc1 .Lstg_done_1

.Lstg_done_1:
	s_mov_b64 s[0:1], s[84:85]
	s_waitcnt vmcnt(0)
	v_mov_b32_e32 v2, v0
	s_load_dwordx2 s[4:5], s[0:1], 0x70
	s_load_dword s0, s[90:91], 0x0
	v_mov_b32_e32 v2, s60
	ds_read_b32 v2, v2
	s_mov_b32 s1, s77
	s_waitcnt lgkmcnt(0)
	v_cmp_eq_u32_e32 vcc, 0, v2
	s_cbranch_vccnz .LBB0_560
	v_mov_b32_e32 v2, s61
	ds_read_b32 v2, v2
	v_mov_b32_e32 v3, s62
	ds_read_b32 v3, v3
	s_waitcnt lgkmcnt(1)
	v_readfirstlane_b32 s1, v2
	s_lshl_b32 s1, s1, 3
	s_waitcnt lgkmcnt(0)
	v_readfirstlane_b32 s2, v3
	s_add_i32 s1, s1, s2

.Lstg_done_2:
	s_mov_b64 s[0:1], s[84:85]
	s_waitcnt vmcnt(0)
	v_mov_b32_e32 v2, v0
	s_load_dwordx2 s[4:5], s[0:1], 0x70
	s_load_dword s3, s[90:91], 0x0
	v_mov_b32_e32 v2, s60
	ds_read_b32 v2, v2
	s_mov_b32 s30, s77
	s_waitcnt lgkmcnt(0)
	v_cmp_eq_u32_e32 vcc, 0, v2
	s_cbranch_vccnz .LBB0_661
	v_mov_b32_e32 v2, s61
	ds_read_b32 v2, v2
	v_mov_b32_e32 v3, s62
	ds_read_b32 v3, v3
	s_waitcnt lgkmcnt(1)
	v_readfirstlane_b32 s0, v2
	s_lshl_b32 s0, s0, 3
	s_waitcnt lgkmcnt(0)
	v_readfirstlane_b32 s1, v3
	s_add_i32 s30, s0, s1

; __global__ void __launch_bounds__(NWAVES * 64, 2) fwd(Args args_unused) {
;     ...
;         if (IN(pb + 5)) {
;             { ENV(); pg8::Gemm g{(const bf16*)(ws + WS_ACT), (const bf16*)(ws + WS_W + (size_t)l * W_LAYER + W_DN), M, DM, DFF, LDACT, 0}; pg8::StaticOrder S; S.init(M, DM, G, bx);
.LBB0_739:
	s_cmp_le_i32 s86, s0
	s_cselect_b64 s[2:3], -1, 0
	s_cmp_lt_i32 s0, s87
	s_cselect_b64 s[0:1], -1, 0
	s_and_b64 s[0:1], s[2:3], s[0:1]
	s_andn2_b64 vcc, exec, s[0:1]
	s_cbranch_vccnz .LBB0_269
	v_mov_b32_e32 v2, s61
	ds_read_b32 v2, v2
	s_waitcnt lgkmcnt(0)
	v_readfirstlane_b32 s98, v2
	s_and_b32 s98, s98, 3
	s_cmp_eq_u32 s98, 0
	s_cbranch_scc1 .Lstg_done_3
